# alt_q3 + grid barrier: non-leader workgroups poll the cross-XCD release word directly (one hop less per barrier)
# baseline (speedup 1.0000x reference)
; __device__ __forceinline__ unsigned xb_ld(unsigned* p)              { return __hip_atomic_load(p, __ATOMIC_RELAXED, __HIP_MEMORY_SCOPE_AGENT); }
; __device__ __forceinline__ unsigned xb_add(unsigned* p, unsigned v) { return __hip_atomic_fetch_add(p, v, __ATOMIC_RELAXED, __HIP_MEMORY_SCOPE_AGENT); }
; #define XB_SPIN(cond, bar) do { unsigned _sp = 0; while (cond) { __builtin_amdgcn_s_sleep(1); \
;     if ((++_sp & 255u) == 0u) { if (xb_ld(&(bar)[XB_TMO])) break; if (_sp > XB_SPIN_CAP) { atomicAdd(&(bar)[XB_TMO], 1u); break; } } } } while (0)
; __device__ __forceinline__ void xcd_barrier(const XcdBarrier& b, int tid) {
;     ...
;         const unsigned old = xb_add(&bar[XB_XSUB(b.x)], 1u);
;         const unsigned gen = old / nloc;
;         if (old + 1u == (gen + 1u) * nloc) {
;             __builtin_amdgcn_fence(__ATOMIC_RELEASE, "agent");
;             asm volatile("s_waitcnt vmcnt(0)" ::: "memory");
;             const unsigned og = xb_add(&bar[XB_TOP], 1u);
;             const unsigned tg = og / nx;
;             if (og + 1u == (tg + 1u) * nx) xb_add(&bar[XB_TOPGEN], 1u);
;             else XB_SPIN(xb_ld(&bar[XB_TOPGEN]) == tg, bar);
;             __builtin_amdgcn_fence(__ATOMIC_ACQUIRE, "agent");
;             xb_add(&bar[XB_XGEN(b.x)], 1u);
;             asm volatile("s_waitcnt vmcnt(0)" ::: "memory");
;         } else {
;             XB_SPIN(xb_ld(&bar[XB_XGEN(b.x)]) == gen, bar);
.LBB0_105:
	s_or_b64 exec, exec, s[12:13]
	v_cvt_f32_u32_e32 v5, v3
	s_waitcnt vmcnt(0)
	v_readfirstlane_b32 s3, v4
	v_sub_u32_e32 v4, 0, v3
	v_rcp_iflag_f32_e32 v5, v5
	v_add_u32_e32 v6, s3, v2
	v_mul_f32_e32 v5, 0x4f7ffffe, v5
	v_cvt_u32_f32_e32 v5, v5
	v_mul_lo_u32 v2, v4, v5
	v_mul_hi_u32 v2, v5, v2
	v_add_u32_e32 v2, v5, v2
	v_mul_hi_u32 v2, v6, v2
	v_mul_lo_u32 v4, v2, v3
	v_sub_u32_e32 v4, v6, v4
	v_add_u32_e32 v5, 1, v2
	v_cmp_ge_u32_e32 vcc, v4, v3
	s_nop 1
	v_cndmask_b32_e32 v2, v2, v5, vcc
	v_sub_u32_e32 v5, v4, v3
	v_cndmask_b32_e32 v4, v4, v5, vcc
	v_add_u32_e32 v5, 1, v2
	v_cmp_ge_u32_e32 vcc, v4, v3
	v_add_u32_e32 v4, 1, v6
	s_nop 0
	v_cndmask_b32_e32 v2, v2, v5, vcc
	v_mul_lo_u32 v5, v3, v2
	v_add_u32_e32 v3, v5, v3
	v_cmp_ne_u32_e32 vcc, v4, v3
	s_and_saveexec_b64 s[10:11], vcc
	s_xor_b64 s[10:11], exec, s[10:11]
	s_cbranch_execz .LBB0_119
	s_waitcnt lgkmcnt(0)
	v_mov_b32_e32 v1, 0x3100
	global_load_dword v1, v1, s[6:7] offset:1024 sc1
	s_add_u32 s14, s6, 0x3500
	s_addc_u32 s15, s7, 0
	s_waitcnt vmcnt(0)
	v_cmp_eq_u32_e32 vcc, v1, v2
	s_and_saveexec_b64 s[12:13], vcc
	s_cbranch_execz .LBB0_118
	s_mov_b32 s3, 1
	s_mov_b64 s[16:17], 0
	v_mov_b32_e32 v1, 0
	s_branch .LBB0_109

; __device__ __forceinline__ unsigned xb_ld(unsigned* p)              { return __hip_atomic_load(p, __ATOMIC_RELAXED, __HIP_MEMORY_SCOPE_AGENT); }
; __device__ __forceinline__ unsigned xb_add(unsigned* p, unsigned v) { return __hip_atomic_fetch_add(p, v, __ATOMIC_RELAXED, __HIP_MEMORY_SCOPE_AGENT); }
; #define XB_SPIN(cond, bar) do { unsigned _sp = 0; while (cond) { __builtin_amdgcn_s_sleep(1); \
;     if ((++_sp & 255u) == 0u) { if (xb_ld(&(bar)[XB_TMO])) break; if (_sp > XB_SPIN_CAP) { atomicAdd(&(bar)[XB_TMO], 1u); break; } } } } while (0)
; __device__ __forceinline__ void xcd_barrier(const XcdBarrier& b, int tid) {
;     ...
;         const unsigned old = xb_add(&bar[XB_XSUB(b.x)], 1u);
;         const unsigned gen = old / nloc;
;         if (old + 1u == (gen + 1u) * nloc) {
;             __builtin_amdgcn_fence(__ATOMIC_RELEASE, "agent");
;             asm volatile("s_waitcnt vmcnt(0)" ::: "memory");
;             const unsigned og = xb_add(&bar[XB_TOP], 1u);
;             const unsigned tg = og / nx;
;             if (og + 1u == (tg + 1u) * nx) xb_add(&bar[XB_TOPGEN], 1u);
;             else XB_SPIN(xb_ld(&bar[XB_TOPGEN]) == tg, bar);
;             __builtin_amdgcn_fence(__ATOMIC_ACQUIRE, "agent");
;             xb_add(&bar[XB_XGEN(b.x)], 1u);
;             asm volatile("s_waitcnt vmcnt(0)" ::: "memory");
;         } else {
;             XB_SPIN(xb_ld(&bar[XB_XGEN(b.x)]) == gen, bar);
.LBB0_378:
	s_or_b64 exec, exec, s[10:11]
	v_cvt_f32_u32_e32 v5, v3
	s_waitcnt vmcnt(0)
	v_readfirstlane_b32 s3, v4
	v_sub_u32_e32 v4, 0, v3
	v_rcp_iflag_f32_e32 v5, v5
	v_add_u32_e32 v6, s3, v2
	v_mul_f32_e32 v5, 0x4f7ffffe, v5
	v_cvt_u32_f32_e32 v5, v5
	v_mul_lo_u32 v2, v4, v5
	v_mul_hi_u32 v2, v5, v2
	v_add_u32_e32 v2, v5, v2
	v_mul_hi_u32 v2, v6, v2
	v_mul_lo_u32 v4, v2, v3
	v_sub_u32_e32 v4, v6, v4
	v_add_u32_e32 v5, 1, v2
	v_cmp_ge_u32_e32 vcc, v4, v3
	s_nop 1
	v_cndmask_b32_e32 v2, v2, v5, vcc
	v_sub_u32_e32 v5, v4, v3
	v_cndmask_b32_e32 v4, v4, v5, vcc
	v_add_u32_e32 v5, 1, v2
	v_cmp_ge_u32_e32 vcc, v4, v3
	v_add_u32_e32 v4, 1, v6
	s_nop 0
	v_cndmask_b32_e32 v2, v2, v5, vcc
	v_mul_lo_u32 v5, v3, v2
	v_add_u32_e32 v3, v5, v3
	v_cmp_ne_u32_e32 vcc, v4, v3
	s_and_saveexec_b64 s[8:9], vcc
	s_xor_b64 s[8:9], exec, s[8:9]
	s_cbranch_execz .LBB0_392
	s_waitcnt lgkmcnt(0)
	v_mov_b32_e32 v1, 0x3100
	global_load_dword v1, v1, s[4:5] offset:1024 sc1
	s_add_u32 s12, s4, 0x3500
	s_addc_u32 s13, s5, 0
	s_waitcnt vmcnt(0)
	v_cmp_eq_u32_e32 vcc, v1, v2
	s_and_saveexec_b64 s[10:11], vcc
	s_cbranch_execz .LBB0_391
	s_mov_b32 s3, 1
	s_mov_b64 s[14:15], 0
	v_mov_b32_e32 v1, 0
	s_branch .LBB0_382
